# masked attention tiles folded into the accumulator-init fast path for selected and window branches; barrier pollers read the top generation word
# baseline (speedup 1.0000x reference)
; __device__ __forceinline__ void attn_phase(const Args& a, LAS unsigned char* lds) {
;     ...
;     for (int i = blockIdx.x; i < 1024; i += gridDim.x) {
;         const int c = i & 255, itn = i >> 8, bg = (c & 7) * 2 + (c >> 7), mm = (c >> 3) & 15;
;         const int qb = itn == 0 ? mm : (itn == 1 ? 31 - mm : (itn == 2 ? 32 + mm : 63 - mm));
;         const int b = bg >> 1, g = bg & 1, q0 = qb * 64, cur = qb;
;         const int tq = q0 + 8 * w + (fr & 7);
;         const size_t row = (size_t)b * SQ + tq;
.LBB0_1000:
	s_mov_b32 s60, 0x45800000
	s_mov_b64 s[62:63], 0x4000
	s_mov_b32 s64, 0x3b000000
	s_barrier

; #define LAS __attribute__((address_space(3)))
; template <int MODE, bool FAST, bool DEFER>
; __device__ __forceinline__ void attn_tile(AttnState& st, const LAS bf16_t* Ks, const LAS bf16_t* Vt, int jb, int tq, bool mybit, int fr, int fq, float (&imp)[16], float& prev_t3, bf16x8 (&pfo)[2][2]) {
;     ...
;         const bf16x8 k0 = *(const LAS bf16x8*)(Ks + (sb * 16 + fr) * KSTR + fq * 8);
;         const bf16x8 k1 = *(const LAS bf16x8*)(Ks + (sb * 16 + fr) * KSTR + 32 + fq * 8);
; #pragma unroll
;         for (int ct = 0; ct < 2; ++ct) {
;             f32x4 z = zinit[ct];
;             z = __builtin_amdgcn_mfma_f32_16x16x32_bf16(k0, st.qf[ct][0], z, 0, 0, 0);
;             z = __builtin_amdgcn_mfma_f32_16x16x32_bf16(k1, st.qf[ct][1], z, 0, 0, 0);
;             s[ct][sb] = ISCMP ? z * ATT_QS : z;
;     ...
;             float t = -1e30f;
; #pragma unroll
;             for (int sb = 0; sb < 4; ++sb)
; #pragma unroll
;                 for (int j = 0; j < 4; ++j) t = fmaxf(t, s[ct][sb][j]);
;             t = fmaxf(t, __shfl_xor(t, 16)); t = fmaxf(t, __shfl_xor(t, 32));
;             tz[ct] = t; un[ct] = st.m[ct] < -1e29f;
;             nd[ct] = (t > -1e29f) && (t > ATT_THR || un[ct]);
.Lslc_half2:
	s_waitcnt lgkmcnt(3)
	v_mfma_f32_16x16x32_bf16 v[108:111], v[84:87], v[8:11], v[108:111]
	v_mfma_f32_16x16x32_bf16 v[96:99], v[84:87], v[16:19], v[96:99]
	s_waitcnt lgkmcnt(2)
	v_mfma_f32_16x16x32_bf16 v[116:119], v[88:91], v[8:11], v[116:119]
	v_mfma_f32_16x16x32_bf16 v[100:103], v[88:91], v[16:19], v[100:103]
	s_waitcnt lgkmcnt(1)
	v_mfma_f32_16x16x32_bf16 v[112:115], v[194:197], v[8:11], v[112:115]
	v_mfma_f32_16x16x32_bf16 v[92:95], v[194:197], v[16:19], v[92:95]
	s_waitcnt lgkmcnt(0)
	v_mfma_f32_16x16x32_bf16 v[120:123], v[206:209], v[8:11], v[120:123]
	v_mfma_f32_16x16x32_bf16 v[104:107], v[206:209], v[16:19], v[104:107]
	s_nop 3
	v_max3_f32 v60, v108, s36, v109
	v_max3_f32 v60, v60, v110, v111
	v_max3_f32 v60, v60, v116, v117
	v_max3_f32 v60, v60, v118, v119
	v_max3_f32 v60, v60, v112, v113
	v_max3_f32 v60, v60, v114, v115
	v_max3_f32 v60, v60, v120, v121
	v_max3_f32 v60, v60, v122, v123
	ds_bpermute_b32 v61, v185, v60
	s_waitcnt lgkmcnt(0)
	v_max_f32_e32 v60, v60, v61
	ds_bpermute_b32 v61, v153, v60
	s_waitcnt lgkmcnt(0)
	v_max_f32_e32 v203, v60, v61
	v_cmp_lt_f32_e32 vcc, s96, v203
	s_and_saveexec_b64 s[4:5], vcc
	s_cbranch_execz .LBB0_1145
	v_cmp_nlt_f32_e32 vcc, s95, v203
	s_mov_b64 s[8:9], -1
	s_and_saveexec_b64 s[10:11], vcc
	s_orn2_b64 s[8:9], s[0:1], exec
	s_or_b64 exec, exec, s[10:11]
	s_and_b64 s[8:9], s[8:9], exec

; #define LAS __attribute__((address_space(3)))
; template <int MODE, bool FAST, bool DEFER>
; __device__ __forceinline__ void attn_tile(AttnState& st, const LAS bf16_t* Ks, const LAS bf16_t* Vt, int jb, int tq, bool mybit, int fr, int fq, float (&imp)[16], float& prev_t3, bf16x8 (&pfo)[2][2]) {
;     ...
;     for (int ct = 0; ct < 2; ++ct) { const float nb_ = !FAST ? 0.f : ((MODE == M_SLC && !mybit) ? -1e30f : (st.m[ct] < -1e29f ? 0.f : -st.m[ct])); zinit[ct] = (f32x4){nb_, nb_, nb_, nb_}; }
; #pragma unroll
;     for (int sb = 0; sb < 4; ++sb) {
;         const bf16x8 k0 = *(const LAS bf16x8*)(Ks + (sb * 16 + fr) * KSTR + fq * 8);
;         const bf16x8 k1 = *(const LAS bf16x8*)(Ks + (sb * 16 + fr) * KSTR + 32 + fq * 8);
; #pragma unroll
;         for (int ct = 0; ct < 2; ++ct) {
;             f32x4 z = zinit[ct];
;             z = __builtin_amdgcn_mfma_f32_16x16x32_bf16(k0, st.qf[ct][0], z, 0, 0, 0);
;             z = __builtin_amdgcn_mfma_f32_16x16x32_bf16(k1, st.qf[ct][1], z, 0, 0, 0);
;             s[ct][sb] = ISCMP ? z * ATT_QS : z;
;         }
;     }
;     ...
; #pragma unroll
;         for (int ct = 0; ct < 2; ++ct) {
;             float ls = 0.f;
; #pragma unroll
;             for (int sb = 0; sb < 4; ++sb)
; #pragma unroll
;                 for (int j = 0; j < 4; ++j) { const float pe = __builtin_amdgcn_exp2f(s[ct][sb][j]); s[ct][sb][j] = pe; ls += pe; }
;             st.l[ct] += ls;
;         }
.LBB0_1151:
	v_exp_f32_e32 v108, v108
	v_exp_f32_e32 v109, v109
	v_exp_f32_e32 v110, v110
	v_exp_f32_e32 v111, v111
	v_exp_f32_e32 v116, v116
	v_add_f32_e32 v129, v109, v108
	v_exp_f32_e32 v117, v117
	v_add_f32_e32 v129, v110, v129
	v_exp_f32_e32 v118, v118
	v_add_f32_e32 v129, v111, v129
	v_exp_f32_e32 v119, v119
	v_add_f32_e32 v129, v116, v129
	v_exp_f32_e32 v112, v112
	v_add_f32_e32 v129, v117, v129
	v_exp_f32_e32 v113, v113
	v_add_f32_e32 v129, v118, v129
	v_exp_f32_e32 v114, v114
	v_add_f32_e32 v129, v119, v129
	v_exp_f32_e32 v115, v115
	v_add_f32_e32 v129, v112, v129
	v_exp_f32_e32 v120, v120
	v_add_f32_e32 v129, v113, v129
	v_exp_f32_e32 v121, v121
	v_add_f32_e32 v129, v114, v129
	v_exp_f32_e32 v122, v122
	v_add_f32_e32 v129, v115, v129
	v_exp_f32_e32 v123, v123
	v_add_f32_e32 v129, v120, v129
	v_exp_f32_e32 v96, v96
	v_add_f32_e32 v129, v121, v129
	v_exp_f32_e32 v97, v97
	v_add_f32_e32 v129, v122, v129
	v_exp_f32_e32 v98, v98
	v_add_f32_e32 v129, v123, v129
	v_exp_f32_e32 v99, v99
	v_add_f32_e32 v159, v159, v129
	v_exp_f32_e32 v100, v100
	v_add_f32_e32 v129, v97, v96
	v_exp_f32_e32 v101, v101
	v_add_f32_e32 v129, v98, v129
	v_exp_f32_e32 v102, v102
	v_add_f32_e32 v129, v99, v129
	v_exp_f32_e32 v103, v103
	v_add_f32_e32 v129, v100, v129
	v_exp_f32_e32 v92, v92
	v_add_f32_e32 v129, v101, v129
	v_exp_f32_e32 v93, v93
	v_add_f32_e32 v129, v102, v129
	v_exp_f32_e32 v94, v94
	v_add_f32_e32 v129, v103, v129
	v_exp_f32_e32 v95, v95
	v_add_f32_e32 v129, v92, v129
	v_exp_f32_e32 v104, v104
	v_add_f32_e32 v129, v93, v129
	v_exp_f32_e32 v105, v105
	v_add_f32_e32 v129, v94, v129
	v_exp_f32_e32 v106, v106
	v_add_f32_e32 v129, v95, v129
	v_exp_f32_e32 v107, v107
	v_add_f32_e32 v129, v104, v129
	v_add_f32_e32 v129, v105, v129
	v_add_f32_e32 v129, v106, v129
	v_add_f32_e32 v203, v107, v129
	s_branch .LBB0_1156
.Ldiag_slc:
	v_cmp_gt_f32_e64 s[0:1], s96, v190
	v_cmp_gt_f32_e64 s[4:5], s96, v191
	v_cndmask_b32_e64 v64, -v190, 0, s[0:1]
	v_cndmask_b32_e64 v60, -v191, 0, s[4:5]
	v_cndmask_b32_e64 v64, v227, v64, s[70:71]
	v_cndmask_b32_e64 v60, v227, v60, s[70:71]
	v_add3_u32 v198, v193, v164, v183
	ds_read_b128 v[68:71], v198
	ds_read_b128 v[72:75], v198 offset:2304
	ds_read_b128 v[76:79], v198 offset:4608
	ds_read_b128 v[80:83], v198 offset:6912
	ds_read_b128 v[84:87], v198 offset:64
	ds_read_b128 v[88:91], v198 offset:2368
	ds_read_b128 v[194:197], v198 offset:4672
	ds_read_b128 v[206:209], v198 offset:6976
	v_readlane_b32 s0, v254, 19
	v_readlane_b32 s1, v254, 20
	s_nop 0
	v_cndmask_b32_e64 v108, v227, v64, s[0:1]
	v_cndmask_b32_e64 v96, v227, v60, s[0:1]
	v_readlane_b32 s0, v254, 21
	v_readlane_b32 s1, v254, 22
	s_nop 0
	v_cndmask_b32_e64 v109, v227, v64, s[0:1]
	v_cndmask_b32_e64 v97, v227, v60, s[0:1]
	v_cndmask_b32_e64 v110, v227, v64, s[42:43]
	v_cndmask_b32_e64 v98, v227, v60, s[42:43]
	v_cndmask_b32_e64 v111, v227, v64, s[44:45]
	v_cndmask_b32_e64 v99, v227, v60, s[44:45]
	v_cndmask_b32_e64 v116, v227, v64, s[46:47]
	v_cndmask_b32_e64 v100, v227, v60, s[46:47]
	v_cndmask_b32_e64 v117, v227, v64, s[48:49]
	v_cndmask_b32_e64 v101, v227, v60, s[48:49]
	v_cndmask_b32_e64 v118, v227, v64, s[50:51]
	v_cndmask_b32_e64 v102, v227, v60, s[50:51]
	v_cndmask_b32_e64 v119, v227, v64, s[52:53]
	v_cndmask_b32_e64 v103, v227, v60, s[52:53]
	v_cndmask_b32_e64 v112, v227, v64, s[54:55]
	v_cndmask_b32_e64 v92, v227, v60, s[54:55]
	v_cndmask_b32_e64 v113, v227, v64, s[56:57]
	v_cndmask_b32_e64 v93, v227, v60, s[56:57]
	v_cndmask_b32_e64 v114, v227, v64, s[58:59]
	v_cndmask_b32_e64 v94, v227, v60, s[58:59]
	v_cndmask_b32_e64 v115, v227, v64, s[60:61]
	v_cndmask_b32_e64 v95, v227, v60, s[60:61]
	v_cndmask_b32_e64 v120, v227, v64, s[62:63]
	v_cndmask_b32_e64 v104, v227, v60, s[62:63]
	v_cndmask_b32_e64 v121, v227, v64, s[64:65]
	v_cndmask_b32_e64 v105, v227, v60, s[64:65]
	v_cndmask_b32_e64 v122, v227, v64, s[66:67]
	v_cndmask_b32_e64 v106, v227, v60, s[66:67]
	v_cndmask_b32_e64 v123, v227, v64, s[68:69]
	v_cndmask_b32_e64 v107, v227, v60, s[68:69]
	v_cmp_gt_f32_e64 s[0:1], s96, v190
	s_mov_b64 s[6:7], 0
	s_mov_b64 s[8:9], 0
	s_waitcnt lgkmcnt(7)
	v_mfma_f32_16x16x32_bf16 v[108:111], v[68:71], v[4:7], v[108:111]
	v_mfma_f32_16x16x32_bf16 v[96:99], v[68:71], v[12:15], v[96:99]
	s_waitcnt lgkmcnt(6)
	v_mfma_f32_16x16x32_bf16 v[116:119], v[72:75], v[4:7], v[116:119]
	v_mfma_f32_16x16x32_bf16 v[100:103], v[72:75], v[12:15], v[100:103]
	s_waitcnt lgkmcnt(5)
	v_mfma_f32_16x16x32_bf16 v[112:115], v[76:79], v[4:7], v[112:115]
	v_mfma_f32_16x16x32_bf16 v[92:95], v[76:79], v[12:15], v[92:95]
	s_waitcnt lgkmcnt(4)
	v_mfma_f32_16x16x32_bf16 v[120:123], v[80:83], v[4:7], v[120:123]
	v_mfma_f32_16x16x32_bf16 v[104:107], v[80:83], v[12:15], v[104:107]
	s_branch .Lslc_half2

; __device__ __forceinline__ float sigm(float x) { return __builtin_amdgcn_rcpf(1.f + __builtin_amdgcn_exp2f(-1.4426950408889634f * x)); }
; __device__ __forceinline__ void attn_phase(const Args& a, LAS unsigned char* lds) {
;     ...
; #pragma unroll
;         for (int ct = 0; ct < 2; ++ct) { const int h = g * 4 + 2 * ct + (fr >> 3); float lt = st.l[ct]; lt += __shfl_xor(lt, 16); lt += __shfl_xor(lt, 32);
;             const float gt = sigm(NG[row * 24 + h * 3 + 1]) * (lt > 0.f ? 1.f / lt : 0.f);
; #pragma unroll
;             for (int dt = 0; dt < 4; ++dt)
; #pragma unroll
;                 for (int j = 0; j < 4; ++j) oacc[((ct * 4 + dt) * 4 + j) * 512] += st.o[ct][dt][j] * gt; }
; #pragma unroll
;         for (int ct = 0; ct < 2; ++ct) { st.m[ct] = -1e30f; st.l[ct] = 0.f;
; #pragma unroll
;             for (int dt = 0; dt < 4; ++dt) st.o[ct][dt] = (f32x4){0.f, 0.f, 0.f, 0.f}; }
;         {
;             const int lo = cur - 8 < 0 ? 0 : cur - 8;
;             const u64 hi_m = cur == 63 ? ~0ull : ((1ull << (cur + 1)) - 1ull);
;             const u64 wt = hi_m & ~((1ull << lo) - 1ull);
;             attn_branch<M_WIN>(st, KV + 4 * KVSZ + (size_t)bg * 4096 * 64, KV + 5 * KVSZ + (size_t)bg * 4096 * 64, wt, Ks, Vt, tq, 0ull, cur, fr, fq, imp);
.LBB0_1162:
	global_load_dword v0, v[154:155], off offset:4
	s_waitcnt vmcnt(2)
	ds_read2st64_b32 v[36:37], v162 offset0:192 offset1:200
	ds_read2st64_b32 v[38:39], v162 offset0:208 offset1:216
	s_waitcnt vmcnt(1)
	ds_read2st64_b32 v[40:41], v162 offset0:224 offset1:232
	ds_read2st64_b32 v[42:43], v162 offset0:240 offset1:248
	ds_read2st64_b32 v[60:61], v163 offset0:64 offset1:72
	ds_read2st64_b32 v[62:63], v163 offset0:80 offset1:88
	ds_read2st64_b32 v[64:65], v163 offset0:96 offset1:104
	ds_read2st64_b32 v[66:67], v163 offset0:112 offset1:120
	global_load_dword v68, v[154:155], off offset:28
	ds_bpermute_b32 v3, v185, v159
	ds_bpermute_b32 v2, v185, v158
	s_mov_b32 s60, 0x45800000
	s_mov_b64 s[62:63], 0x4000
	s_mov_b32 s64, 0x3b000000
	s_waitcnt lgkmcnt(0)
	v_pk_add_f32 v[2:3], v[158:159], v[2:3]
	ds_bpermute_b32 v69, v153, v3
	s_waitcnt vmcnt(1)
	v_mul_f32_e32 v0, 0xbfb8aa3b, v0
	v_exp_f32_e32 v0, v0
	s_waitcnt vmcnt(0)
	v_mul_f32_e32 v68, 0xbfb8aa3b, v68
	v_exp_f32_e32 v68, v68
	v_add_f32_e32 v0, 1.0, v0
	v_rcp_f32_e32 v0, v0
	v_add_f32_e32 v68, 1.0, v68
	v_rcp_f32_e32 v70, v68
	ds_bpermute_b32 v68, v153, v2
	s_waitcnt lgkmcnt(0)
	v_pk_add_f32 v[68:69], v[2:3], v[68:69]
	s_nop 0
	v_div_scale_f32 v2, s[0:1], v69, v69, 1.0
	v_rcp_f32_e32 v3, v2
	v_cmp_lt_f32_e64 s[0:1], 0, v68
	v_fma_f32 v71, -v2, v3, 1.0
	v_fmac_f32_e32 v3, v71, v3
	v_div_scale_f32 v71, vcc, 1.0, v69, 1.0
	v_mul_f32_e32 v72, v71, v3
	v_fma_f32 v73, -v2, v72, v71
	v_fmac_f32_e32 v72, v73, v3
	v_fma_f32 v2, -v2, v72, v71
	v_div_fmas_f32 v2, v2, v3, v72
	v_div_fixup_f32 v2, v2, v69, 1.0
	v_cmp_lt_f32_e32 vcc, 0, v69
	v_mov_b32_e32 v3, 0
	s_nop 0
	v_cndmask_b32_e32 v2, 0, v2, vcc
	v_mul_f32_e32 v0, v2, v0
	v_fma_f32 v2, v44, v0, v36
	v_fmac_f32_e32 v37, v45, v0
	ds_write2st64_b32 v162, v2, v37 offset0:192 offset1:200
	v_fma_f32 v2, v46, v0, v38
	v_fmac_f32_e32 v39, v47, v0
	ds_write2st64_b32 v162, v2, v39 offset0:208 offset1:216
	v_fma_f32 v2, v48, v0, v40
	v_fmac_f32_e32 v41, v49, v0
	ds_write2st64_b32 v162, v2, v41 offset0:224 offset1:232
	v_fma_f32 v2, v50, v0, v42
	v_fmac_f32_e32 v43, v51, v0
	ds_write2st64_b32 v162, v2, v43 offset0:240 offset1:248
	v_fma_f32 v2, v52, v0, v60
	v_fmac_f32_e32 v61, v53, v0
	ds_write2st64_b32 v163, v2, v61 offset0:64 offset1:72
	v_fma_f32 v2, v54, v0, v62
	v_fmac_f32_e32 v63, v55, v0
	ds_write2st64_b32 v163, v2, v63 offset0:80 offset1:88
	v_fma_f32 v2, v56, v0, v64
	v_fmac_f32_e32 v65, v57, v0
	ds_write2st64_b32 v163, v2, v65 offset0:96 offset1:104
	v_fma_f32 v2, v58, v0, v66
	v_fmac_f32_e32 v67, v59, v0
	v_div_scale_f32 v0, s[2:3], v68, v68, 1.0
	ds_write2st64_b32 v163, v2, v67 offset0:112 offset1:120
	v_rcp_f32_e32 v2, v0
	v_mov_b32_e32 v59, 0
	v_mov_b32_e32 v58, 0
	v_mov_b32_e32 v57, 0
	v_fma_f32 v36, -v0, v2, 1.0
	v_fmac_f32_e32 v2, v36, v2
	v_div_scale_f32 v36, vcc, 1.0, v68, 1.0
	v_mul_f32_e32 v37, v36, v2
	v_fma_f32 v38, -v0, v37, v36
	v_fmac_f32_e32 v37, v38, v2
	v_fma_f32 v0, -v0, v37, v36
	v_div_fmas_f32 v0, v0, v2, v37
	ds_read2st64_b32 v[36:37], v163 offset0:128 offset1:136
	v_div_fixup_f32 v0, v0, v68, 1.0
	v_cndmask_b32_e64 v0, 0, v0, s[0:1]
	v_mul_f32_e32 v0, v0, v70
	s_max_i32 s0, s37, 8
	s_waitcnt lgkmcnt(0)
	v_fma_f32 v2, v28, v0, v36
	v_fmac_f32_e32 v37, v29, v0
	ds_read2st64_b32 v[28:29], v163 offset0:144 offset1:152
	ds_write2st64_b32 v163, v2, v37 offset0:128 offset1:136
	s_add_i32 s2, s0, -8
	s_add_i32 s0, s37, 1
	s_lshl_b64 s[0:1], -1, s0
	s_waitcnt lgkmcnt(1)
	v_fma_f32 v2, v30, v0, v28
	v_fmac_f32_e32 v29, v31, v0
	ds_write2st64_b32 v163, v2, v29 offset0:144 offset1:152
	ds_read2st64_b32 v[28:29], v163 offset0:160 offset1:168
	s_not_b64 s[0:1], s[0:1]
	s_cmp_lg_u32 s37, 63
	s_cselect_b32 s1, s1, -1
	s_cselect_b32 s0, s0, -1
	s_waitcnt lgkmcnt(0)
	v_fma_f32 v2, v32, v0, v28
	v_fmac_f32_e32 v29, v33, v0
	ds_write2st64_b32 v163, v2, v29 offset0:160 offset1:168
	ds_read2st64_b32 v[28:29], v163 offset0:176 offset1:184
	s_lshl_b64 s[2:3], -1, s2
	s_and_b64 s[0:1], s[0:1], s[2:3]
	s_cmp_eq_u64 s[0:1], 0
	v_mov_b32_e32 v33, 0
	s_waitcnt lgkmcnt(0)
	v_fma_f32 v2, v34, v0, v28
	v_fmac_f32_e32 v29, v35, v0
	ds_write2st64_b32 v163, v2, v29 offset0:176 offset1:184
	ds_read2st64_b32 v[28:29], v163 offset0:192 offset1:200
	v_mov_b32_e32 v35, 0
	v_mov_b32_e32 v34, 0
	v_mov_b32_e32 v32, 0
	v_mov_b32_e32 v31, 0
	s_waitcnt lgkmcnt(0)
	v_fma_f32 v2, v24, v0, v28
	v_fmac_f32_e32 v29, v25, v0
	ds_read2st64_b32 v[24:25], v163 offset0:208 offset1:216
	ds_write2st64_b32 v163, v2, v29 offset0:192 offset1:200
	v_mov_b32_e32 v30, 0
	v_mov_b32_e32 v29, 0
	v_mov_b32_e32 v28, 0
	s_waitcnt lgkmcnt(1)
	v_fma_f32 v2, v26, v0, v24
	v_fmac_f32_e32 v25, v27, v0
	ds_write2st64_b32 v163, v2, v25 offset0:208 offset1:216
	ds_read2st64_b32 v[24:25], v163 offset0:224 offset1:232
	v_mov_b32_e32 v27, 0
	v_mov_b32_e32 v26, 0
	v_mov_b32_e32 v56, 0
	v_mov_b32_e32 v55, 0
	s_waitcnt lgkmcnt(0)
	v_fma_f32 v2, v20, v0, v24
	v_fmac_f32_e32 v25, v21, v0
	ds_read2st64_b32 v[20:21], v163 offset0:240 offset1:248
	ds_write2st64_b32 v163, v2, v25 offset0:224 offset1:232
	v_mov_b32_e32 v25, 0
	v_mov_b32_e32 v24, 0
	v_mov_b32_e32 v54, 0
	s_waitcnt lgkmcnt(1)
	v_fma_f32 v2, v22, v0, v20
	v_fmac_f32_e32 v21, v23, v0
	ds_write2st64_b32 v163, v2, v21 offset0:240 offset1:248
	v_mov_b32_e32 v0, v199
	v_mov_b32_e32 v2, 0
	v_mov_b32_e32 v23, 0
	v_mov_b32_e32 v22, 0
	v_mov_b32_e32 v21, 0
	v_mov_b32_e32 v20, 0
	v_mov_b32_e32 v53, 0
	v_mov_b32_e32 v52, 0
	v_mov_b32_e32 v51, 0
	v_mov_b32_e32 v50, 0
	v_mov_b32_e32 v49, 0
	v_mov_b32_e32 v48, 0
	v_mov_b32_e32 v39, 0
	v_mov_b32_e32 v38, 0
	v_mov_b32_e32 v37, 0
	v_mov_b32_e32 v36, 0
	s_cbranch_scc1 .LBB0_1001
; template <int MODE>
; __device__ __forceinline__ void attn_branch(AttnState& st, const bf16_t* __restrict__ Kg, const bf16_t* __restrict__ Vg, u64 tiles, LAS bf16_t* KsB, LAS bf16_t* VtB,
;                                             int tq, u64 mymask, int cur, int fr, int fq, float (&imp)[16]) {
;     ...
;     int jb = __builtin_ctzll(tiles); tiles &= tiles - 1ull;
;     u32x4v kr = *(const u32x4v*)(Kg + (size_t)(jb * 64 + kkey) * 64 + kch * 8), vr = (u32x4v){0u, 0u, 0u, 0u};
;     if (MODE != M_CMP1) vr = *(const u32x4v*)(Vg + (size_t)(jb * 64 + kkey) * 64 + kch * 8);
;     int pb = 0, vb = 0, vprev = 0; bool have = false;
;     bf16x8 pf[2][2];
; __device__ __forceinline__ void attn_phase(const Args& a, LAS unsigned char* lds) {
;     ...
;         {
;             const int lo = cur - 8 < 0 ? 0 : cur - 8;
;             const u64 hi_m = cur == 63 ? ~0ull : ((1ull << (cur + 1)) - 1ull);
;             const u64 wt = hi_m & ~((1ull << lo) - 1ull);
;             attn_branch<M_WIN>(st, KV + 4 * KVSZ + (size_t)bg * 4096 * 64, KV + 5 * KVSZ + (size_t)bg * 4096 * 64, wt, Ks, Vt, tq, 0ull, cur, fr, fq, imp);
	s_lshl_b32 s2, s14, 1
	v_readlane_b32 s3, v252, 27
	s_add_u32 s4, s3, s2
	v_readlane_b32 s3, v252, 28
	s_addc_u32 s5, s3, 0
	v_readlane_b32 s3, v252, 29
	s_add_u32 s6, s3, s2
	v_readlane_b32 s2, v252, 30
	v_ashrrev_i32_e32 v160, 3, v0
	s_addc_u32 s7, s2, 0
	s_ff1_i32_b64 s2, s[0:1]
	v_lshl_add_u32 v2, s2, 6, v160
	v_ashrrev_i32_e32 v3, 31, v2
	v_lshlrev_b32_e32 v0, 3, v0
	v_lshlrev_b64 v[2:3], 7, v[2:3]
	v_and_b32_e32 v0, 56, v0
	v_lshl_add_u64 v[20:21], s[6:7], 0, v[2:3]
	v_lshlrev_b32_e32 v0, 1, v0
	v_lshl_add_u64 v[20:21], v[20:21], 0, v[0:1]
	v_lshl_add_u64 v[2:3], s[4:5], 0, v[2:3]
	v_lshl_add_u64 v[2:3], v[2:3], 0, v[0:1]
	global_load_dwordx4 v[40:43], v[20:21], off
	global_load_dwordx4 v[44:47], v[2:3], off
	s_add_u32 s8, s0, -1
	s_movk_i32 s3, 0x48
	v_mov_b32_e32 v36, v1
	v_mov_b32_e32 v37, v1
	v_mov_b32_e32 v38, v1
	v_mov_b32_e32 v39, v1
	s_addc_u32 s9, s1, -1
	v_mul_lo_u32 v2, v160, s3
	v_mov_b64_e32 v[50:51], v[38:39]
	v_mov_b64_e32 v[54:55], v[38:39]
	v_mov_b64_e32 v[58:59], v[38:39]
	v_mov_b64_e32 v[20:21], v[36:37]
	v_mov_b64_e32 v[24:25], v[36:37]
	v_mov_b64_e32 v[28:29], v[36:37]
	v_mov_b64_e32 v[32:33], v[36:37]
	s_and_b64 s[0:1], s[8:9], s[0:1]
	v_lshl_add_u64 v[96:97], s[6:7], 0, v[0:1]
	v_lshl_add_u64 v[98:99], s[4:5], 0, v[0:1]
	s_add_i32 s14, s37, -8
	v_add_u32_e32 v161, 0xfffffe00, v152
	s_mov_b32 s15, 0
	v_mov_b32_e32 v191, 0
	v_mov_b32_e32 v189, 0xf149f2ca
	v_mov_b32_e32 v187, 0
	v_lshlrev_b32_e32 v188, 1, v2
	v_mov_b32_e32 v190, 0xf149f2ca
	v_mov_b32_e32 v2, 0
	v_mov_b64_e32 v[48:49], v[36:37]
	v_mov_b64_e32 v[52:53], v[36:37]
	v_mov_b64_e32 v[56:57], v[36:37]
	v_mov_b64_e32 v[22:23], v[38:39]
	v_mov_b64_e32 v[26:27], v[38:39]
	v_mov_b64_e32 v[30:31], v[38:39]
	v_mov_b64_e32 v[34:35], v[38:39]
	v_or_b32_e32 v60, 2, v126
	v_cmp_le_i32_e64 s[42:43], v60, v148
	v_or_b32_e32 v60, 3, v126
	v_cmp_le_i32_e64 s[44:45], v60, v148
	v_or_b32_e32 v60, 16, v126
	v_cmp_le_i32_e64 s[46:47], v60, v148
	v_or_b32_e32 v60, 17, v126
	v_cmp_le_i32_e64 s[48:49], v60, v148
	v_or_b32_e32 v60, 18, v126
	v_cmp_le_i32_e64 s[50:51], v60, v148
	v_or_b32_e32 v60, 19, v126
	v_cmp_le_i32_e64 s[52:53], v60, v148
	v_or_b32_e32 v60, 32, v126
	v_cmp_le_i32_e64 s[54:55], v60, v148
	v_or_b32_e32 v60, 33, v126
	v_cmp_le_i32_e64 s[56:57], v60, v148
	v_or_b32_e32 v60, 34, v126
	v_cmp_le_i32_e64 s[58:59], v60, v148
	v_or_b32_e32 v60, 35, v126
	v_cmp_le_i32_e64 s[60:61], v60, v148
	v_or_b32_e32 v60, 48, v126
	v_cmp_le_i32_e64 s[62:63], v60, v148
	v_or_b32_e32 v60, 49, v126
	v_cmp_le_i32_e64 s[64:65], v60, v148
	v_or_b32_e32 v60, 50, v126
	v_cmp_le_i32_e64 s[66:67], v60, v148
	v_or_b32_e32 v60, 51, v126
	v_cmp_le_i32_e64 s[68:69], v60, v148

; #define LAS __attribute__((address_space(3)))
; template <int MODE, bool FAST, bool DEFER>
; __device__ __forceinline__ void attn_tile(AttnState& st, const LAS bf16_t* Ks, const LAS bf16_t* Vt, int jb, int tq, bool mybit, int fr, int fq, float (&imp)[16], float& prev_t3, bf16x8 (&pfo)[2][2]) {
;     ...
;     for (int ct = 0; ct < 2; ++ct) { const float nb_ = !FAST ? 0.f : ((MODE == M_SLC && !mybit) ? -1e30f : (st.m[ct] < -1e29f ? 0.f : -st.m[ct])); zinit[ct] = (f32x4){nb_, nb_, nb_, nb_}; }
; #pragma unroll
;     for (int sb = 0; sb < 4; ++sb) {
;         const bf16x8 k0 = *(const LAS bf16x8*)(Ks + (sb * 16 + fr) * KSTR + fq * 8);
;         const bf16x8 k1 = *(const LAS bf16x8*)(Ks + (sb * 16 + fr) * KSTR + 32 + fq * 8);
; #pragma unroll
;         for (int ct = 0; ct < 2; ++ct) {
;             f32x4 z = zinit[ct];
;             z = __builtin_amdgcn_mfma_f32_16x16x32_bf16(k0, st.qf[ct][0], z, 0, 0, 0);
;             z = __builtin_amdgcn_mfma_f32_16x16x32_bf16(k1, st.qf[ct][1], z, 0, 0, 0);
;             s[ct][sb] = ISCMP ? z * ATT_QS : z;
;         }
;     }
;     unsigned vbits = 0;
;     if (!FAST) {
; #pragma unroll
;         for (int sb = 0; sb < 4; ++sb)
; #pragma unroll
;             for (int j = 0; j < 4; ++j) {
;                 const int kidx = jb * 64 + sb * 16 + fq * 4 + j;
;                 bool v;
;                 if (ISCMP) v = (16 * kidx + 31 <= tq);
;                 else if (MODE == M_SLC) v = mybit && (kidx <= tq);
;                 else v = (kidx <= tq) && (tq - kidx < 512);
;                 vbits |= (v ? 1u : 0u) << (sb * 4 + j);
;             }
;     }
; template <int MODE>
; __device__ __forceinline__ void attn_branch(AttnState& st, const bf16_t* __restrict__ Kg, const bf16_t* __restrict__ Vg, u64 tiles, LAS bf16_t* KsB, LAS bf16_t* VtB,
;                                             int tq, u64 mymask, int cur, int fr, int fq, float (&imp)[16]) {
;     ...
;                 const bool fast = (MODE == M_SLC) ? (jb != cur) : (jb != cur && jb != cur - 8);
;                 if (fast) attn_tile<MODE, true, true>(st, Ks, Vt, jb, tq, mybit, fr, fq, imp, prev_t3, pf); else attn_tile<MODE, false, true>(st, Ks, Vt, jb, tq, mybit, fr, fq, imp, prev_t3, pf);
.LBB0_1167:
	s_cmp_lg_u32 s2, s37
	s_cselect_b64 s[0:1], -1, 0
	s_cmp_lg_u32 s2, s14
	s_cselect_b64 s[4:5], -1, 0
	s_and_b64 s[4:5], s[0:1], s[4:5]
	s_mov_b64 s[0:1], -1
	s_andn2_b64 vcc, exec, s[4:5]
	v_add3_u32 v193, v3, v164, v183
	s_waitcnt lgkmcnt(0)
	s_barrier
	s_cbranch_vccz .LBB0_1171
	ds_read_b128 v[194:197], v193
	ds_read_b128 v[210:213], v193 offset:2304
	ds_read_b128 v[234:237], v193 offset:4608
	ds_read_b128 v[244:247], v193 offset:6912
	ds_read_b128 v[206:209], v193 offset:64
	ds_read_b128 v[230:233], v193 offset:2368
	ds_read_b128 v[238:241], v193 offset:4672
	ds_read_b128 v[100:103], v193 offset:6976
	v_cmp_gt_f32_e64 s[4:5], s96, v189
	v_cmp_gt_f32_e64 s[0:1], s96, v190
	v_cndmask_b32_e64 v104, -v189, 0, s[4:5]
	v_cndmask_b32_e64 v105, -v190, 0, s[0:1]
	s_cmp_eq_u32 s2, s37
	s_cbranch_scc0 .Ldiag_win_lo
	v_readlane_b32 s6, v254, 19
	v_readlane_b32 s7, v254, 20
	s_nop 0
	v_cndmask_b32_e64 v80, v227, v104, s[6:7]
	v_cndmask_b32_e64 v72, v227, v105, s[6:7]
	v_readlane_b32 s6, v254, 21
	v_readlane_b32 s7, v254, 22
	s_nop 0
	v_cndmask_b32_e64 v81, v227, v104, s[6:7]
	v_cndmask_b32_e64 v73, v227, v105, s[6:7]
	v_cndmask_b32_e64 v82, v227, v104, s[42:43]
	v_cndmask_b32_e64 v74, v227, v105, s[42:43]
	v_cndmask_b32_e64 v83, v227, v104, s[44:45]
	v_cndmask_b32_e64 v75, v227, v105, s[44:45]
	v_cndmask_b32_e64 v84, v227, v104, s[46:47]
	v_cndmask_b32_e64 v64, v227, v105, s[46:47]
	v_cndmask_b32_e64 v85, v227, v104, s[48:49]
	v_cndmask_b32_e64 v65, v227, v105, s[48:49]
	v_cndmask_b32_e64 v86, v227, v104, s[50:51]
	v_cndmask_b32_e64 v66, v227, v105, s[50:51]
	v_cndmask_b32_e64 v87, v227, v104, s[52:53]
	v_cndmask_b32_e64 v67, v227, v105, s[52:53]
	v_cndmask_b32_e64 v76, v227, v104, s[54:55]
	v_cndmask_b32_e64 v60, v227, v105, s[54:55]
	v_cndmask_b32_e64 v77, v227, v104, s[56:57]
	v_cndmask_b32_e64 v61, v227, v105, s[56:57]
	v_cndmask_b32_e64 v78, v227, v104, s[58:59]
	v_cndmask_b32_e64 v62, v227, v105, s[58:59]
	v_cndmask_b32_e64 v79, v227, v104, s[60:61]
	v_cndmask_b32_e64 v63, v227, v105, s[60:61]
	v_cndmask_b32_e64 v88, v227, v104, s[62:63]
	v_cndmask_b32_e64 v68, v227, v105, s[62:63]
	v_cndmask_b32_e64 v89, v227, v104, s[64:65]
	v_cndmask_b32_e64 v69, v227, v105, s[64:65]
	v_cndmask_b32_e64 v90, v227, v104, s[66:67]
	v_cndmask_b32_e64 v70, v227, v105, s[66:67]
	v_cndmask_b32_e64 v91, v227, v104, s[68:69]
	v_cndmask_b32_e64 v71, v227, v105, s[68:69]
	s_branch .Ldiag_win_mm
.Ldiag_win_lo:
	v_readlane_b32 s6, v254, 19
	v_readlane_b32 s7, v254, 20
	s_nop 0
	v_cndmask_b32_e64 v80, v104, v227, s[6:7]
	v_cndmask_b32_e64 v72, v105, v227, s[6:7]
	v_readlane_b32 s6, v254, 21
	v_readlane_b32 s7, v254, 22
	s_nop 0
	v_cndmask_b32_e64 v81, v104, v227, s[6:7]
	v_cndmask_b32_e64 v73, v105, v227, s[6:7]
	v_cndmask_b32_e64 v82, v104, v227, s[42:43]
	v_cndmask_b32_e64 v74, v105, v227, s[42:43]
	v_cndmask_b32_e64 v83, v104, v227, s[44:45]
	v_cndmask_b32_e64 v75, v105, v227, s[44:45]
	v_cndmask_b32_e64 v84, v104, v227, s[46:47]
	v_cndmask_b32_e64 v64, v105, v227, s[46:47]
	v_cndmask_b32_e64 v85, v104, v227, s[48:49]
	v_cndmask_b32_e64 v65, v105, v227, s[48:49]
	v_cndmask_b32_e64 v86, v104, v227, s[50:51]
	v_cndmask_b32_e64 v66, v105, v227, s[50:51]
	v_cndmask_b32_e64 v87, v104, v227, s[52:53]
	v_cndmask_b32_e64 v67, v105, v227, s[52:53]
	v_cndmask_b32_e64 v76, v104, v227, s[54:55]
	v_cndmask_b32_e64 v60, v105, v227, s[54:55]
	v_cndmask_b32_e64 v77, v104, v227, s[56:57]
	v_cndmask_b32_e64 v61, v105, v227, s[56:57]
	v_cndmask_b32_e64 v78, v104, v227, s[58:59]
	v_cndmask_b32_e64 v62, v105, v227, s[58:59]
	v_cndmask_b32_e64 v79, v104, v227, s[60:61]
	v_cndmask_b32_e64 v63, v105, v227, s[60:61]
	v_cndmask_b32_e64 v88, v104, v227, s[62:63]
	v_cndmask_b32_e64 v68, v105, v227, s[62:63]
	v_cndmask_b32_e64 v89, v104, v227, s[64:65]
	v_cndmask_b32_e64 v69, v105, v227, s[64:65]
	v_cndmask_b32_e64 v90, v104, v227, s[66:67]
	v_cndmask_b32_e64 v70, v105, v227, s[66:67]
	v_cndmask_b32_e64 v91, v104, v227, s[68:69]
	v_cndmask_b32_e64 v71, v105, v227, s[68:69]
.Ldiag_win_mm:
	s_mov_b64 s[2:3], 0
	s_mov_b64 s[6:7], 0
	s_waitcnt lgkmcnt(7)
	v_mfma_f32_16x16x32_bf16 v[80:83], v[194:197], v[4:7], v[80:83]
	v_mfma_f32_16x16x32_bf16 v[72:75], v[194:197], v[12:15], v[72:75]
	s_waitcnt lgkmcnt(6)
	v_mfma_f32_16x16x32_bf16 v[84:87], v[210:213], v[4:7], v[84:87]
	v_mfma_f32_16x16x32_bf16 v[64:67], v[210:213], v[12:15], v[64:67]
	s_waitcnt lgkmcnt(5)
	v_mfma_f32_16x16x32_bf16 v[76:79], v[234:237], v[4:7], v[76:79]
	v_mfma_f32_16x16x32_bf16 v[60:63], v[234:237], v[12:15], v[60:63]
	s_waitcnt lgkmcnt(4)
	v_mfma_f32_16x16x32_bf16 v[88:91], v[244:247], v[4:7], v[88:91]
	v_mfma_f32_16x16x32_bf16 v[68:71], v[244:247], v[12:15], v[68:71]
	s_waitcnt lgkmcnt(0)
	v_mfma_f32_16x16x32_bf16 v[80:83], v[206:209], v[8:11], v[80:83]
	v_mfma_f32_16x16x32_bf16 v[84:87], v[230:233], v[8:11], v[84:87]
	v_mfma_f32_16x16x32_bf16 v[76:79], v[238:241], v[8:11], v[76:79]
	v_mfma_f32_16x16x32_bf16 v[88:91], v[100:103], v[8:11], v[88:91]
	v_mfma_f32_16x16x32_bf16 v[72:75], v[206:209], v[16:19], v[72:75]
	v_mfma_f32_16x16x32_bf16 v[64:67], v[230:233], v[16:19], v[64:67]
	v_mfma_f32_16x16x32_bf16 v[60:63], v[238:241], v[16:19], v[60:63]
	v_mfma_f32_16x16x32_bf16 v[68:71], v[100:103], v[16:19], v[68:71]
	s_nop 3
	v_max3_f32 v3, v80, s36, v81
	v_max3_f32 v3, v3, v82, v83
	v_max3_f32 v3, v3, v84, v85
	v_max3_f32 v3, v3, v86, v87
	v_max3_f32 v3, v3, v76, v77
	v_max3_f32 v3, v3, v78, v79
	v_max3_f32 v3, v3, v88, v89
	v_max3_f32 v3, v3, v90, v91
	s_branch .Lwin_max

; template <int MODE, bool FAST, bool DEFER>
; __device__ __forceinline__ void attn_tile(AttnState& st, const LAS bf16_t* Ks, const LAS bf16_t* Vt, int jb, int tq, bool mybit, int fr, int fq, float (&imp)[16], float& prev_t3, bf16x8 (&pfo)[2][2]) {
;     ...
;             for (int sb = 0; sb < 4; ++sb)
; #pragma unroll
;                 for (int j = 0; j < 4; ++j) t = fmaxf(t, s[ct][sb][j]);
;             t = fmaxf(t, __shfl_xor(t, 16)); t = fmaxf(t, __shfl_xor(t, 32));
;             tz[ct] = t; un[ct] = st.m[ct] < -1e29f;
;             nd[ct] = (t > -1e29f) && (t > ATT_THR || un[ct]);
;         }
;         if (__builtin_amdgcn_ballot_w64(nd[0] || nd[1]) != 0ull) {
.Lwin_max:
	ds_bpermute_b32 v92, v185, v3
	s_waitcnt lgkmcnt(0)
	v_max_f32_e32 v92, v92, v92
	v_max_f32_e32 v3, v3, v92
	ds_bpermute_b32 v92, v153, v3
	s_waitcnt lgkmcnt(0)
	v_max_f32_e32 v92, v92, v92
	v_max_f32_e32 v92, v3, v92
	v_cmp_lt_f32_e32 vcc, s96, v92
	s_and_saveexec_b64 s[8:9], vcc
	s_cbranch_execz .LBB0_1176
	v_cmp_nlt_f32_e32 vcc, s95, v92
	s_mov_b64 s[6:7], -1
	s_and_saveexec_b64 s[12:13], vcc
	s_orn2_b64 s[6:7], s[4:5], exec
	s_or_b64 exec, exec, s[12:13]
	s_and_b64 s[6:7], s[6:7], exec
